# gdn chain loader steady-state pacing s_sleep 3 (was 2) on top of the paced gla loader
# speedup vs baseline: 1.0034x; 1.0034x over previous
; #define LBAR() do { asm volatile("s_waitcnt lgkmcnt(0)" ::: "memory"); __builtin_amdgcn_s_barrier(); asm volatile("" ::: "memory"); } while (0)
; #define WAITV(N_) asm volatile("s_waitcnt vmcnt(" #N_ ")" ::: "memory")
; #define ISSUE_XG(s_) do { const unsigned char* g_ = A.blob + (unit0 + CHUNK_OF(s_)) * BLOB + lane * 16; const unsigned l_ = lds0 + ((s_) & 1) * C_BUF; \
;         _Pragma("unroll") for (int k = 0; k < 8; ++k) { const unsigned o_ = (lw + 4 * k) * 1024; DMA1(g_ + o_, l_ + o_); __builtin_amdgcn_s_sleep(LOADER_PACE); } } while (0)
; #define WAITV(N_) asm volatile("s_waitcnt vmcnt(" #N_ ")" ::: "memory")
; #define ISSUE_XG(s_) do { const unsigned char* g_ = A.blobA + (unit0 + CHUNK_OF(s_)) * BLOBA + qo + lane * 16; const unsigned l_ = lds0 + ((s_) & 1) * CB_BUF; \
;         _Pragma("unroll") for (int k = 0; k < 4; ++k) { const unsigned o_ = (lw + 4 * k) * 1024; DMA1(g_ + o_, l_ + o_); } } while (0)
; __device__ __forceinline__ void gdn_chain_unit(LAS unsigned char* lds, const GdnChainArgs& A, int item, int half) {
;     ...
;         if (!(flags & 4)) { ISSUE_XG(0); ISSUE_YG(0); ISSUE_XG(1); }
;         WAITV(0);
;         LBAR();
;         for (int s = 0; s < NCH; ++s) {
;             if (s + 1 < NCH && !(flags & 4)) ISSUE_YG(s + 1);
;             LBAR();
;             if (s + 2 < NCH && !(flags & 4)) ISSUE_XG(s + 2);
;             if (s <= NCH - 3 && !probe) WAITV(8); else WAITV(0);
;             LBAR();
;         }
.LBB0_661:
	v_readlane_b32 vcc_lo, v254, 44
	s_add_i32 s81, s80, 2
	s_add_i32 s78, s78, -1
	v_readlane_b32 vcc_hi, v254, 45
	s_and_b64 s[82:83], vcc, exec
	s_cselect_b32 s81, s81, s78
	v_readlane_b32 s94, v254, 46
	v_readlane_b32 s95, v254, 47
	s_add_u32 s81, s94, s81
	s_addc_u32 s82, s95, 0
	s_mul_i32 s84, s82, 0x18800
	v_mad_u64_u32 v[4:5], s[82:83], s81, v172, v[2:3]
	s_bitcmp1_b32 s80, 0
	v_add_u32_e32 v5, s84, v5
	s_cselect_b32 s80, s76, 0
	s_waitcnt lgkmcnt(0)
	s_barrier
	v_lshl_add_u64 v[6:7], v[4:5], 0, s[34:35]
	s_add_i32 s81, s80, s34
	s_mov_b32 m0, s81
	s_nop 0
	global_load_lds_dwordx4 v[6:7], off
	v_lshl_add_u64 v[6:7], v[4:5], 0, s[4:5]
	s_add_i32 s81, s80, s4
	s_sleep 3
	s_mov_b32 m0, s81
	s_nop 0
	global_load_lds_dwordx4 v[6:7], off
	v_lshl_add_u64 v[6:7], v[4:5], 0, s[6:7]
	s_add_i32 s81, s80, s6
	s_sleep 3
	s_mov_b32 m0, s81
	s_nop 0
	global_load_lds_dwordx4 v[6:7], off
	v_lshl_add_u64 v[6:7], v[4:5], 0, s[36:37]
	s_add_i32 s81, s80, s36
	s_sleep 3
	s_mov_b32 m0, s81
	s_nop 0
	global_load_lds_dwordx4 v[6:7], off
	v_lshl_add_u64 v[6:7], v[4:5], 0, s[38:39]
	s_add_i32 s81, s80, s38
	s_sleep 3
	s_mov_b32 m0, s81
	s_nop 0
	global_load_lds_dwordx4 v[6:7], off
	v_lshl_add_u64 v[6:7], v[4:5], 0, s[40:41]
	s_add_i32 s81, s80, s40
	s_sleep 3
	s_mov_b32 m0, s81
	s_nop 0
	global_load_lds_dwordx4 v[6:7], off
	s_sleep 3
	v_lshl_add_u64 v[6:7], v[4:5], 0, s[42:43]
	s_add_i32 s81, s80, s42
	s_mov_b32 m0, s81
	s_nop 0
	global_load_lds_dwordx4 v[6:7], off
	s_sleep 3
	v_lshl_add_u64 v[4:5], v[4:5], 0, s[44:45]
	s_add_i32 s80, s80, s44
	s_mov_b32 m0, s80
	s_nop 0
	global_load_lds_dwordx4 v[4:5], off
	s_sleep 3
	s_waitcnt vmcnt(8)
	s_waitcnt lgkmcnt(0)
	s_barrier
	s_cmp_eq_u32 s78, 0
	s_mov_b32 s80, s79
	s_cbranch_scc1 .LBB0_664
.LBB0_662:
	s_add_i32 s79, s80, 1
	s_and_b64 s[2:3], vcc, exec
	s_cselect_b32 s2, s79, s78
	s_add_u32 s2, s94, s2
	s_addc_u32 s3, s95, 0
	s_mul_i32 s81, s3, 0x18800
	v_mad_u64_u32 v[4:5], s[2:3], s2, v172, v[2:3]
	s_bitcmp1_b32 s79, 0
	v_add_u32_e32 v5, s81, v5
	s_cselect_b32 s81, s76, 0
	v_lshl_add_u64 v[6:7], v[4:5], 0, s[46:47]
	s_add_i32 s2, s81, s46
	s_mov_b32 m0, s2
	s_nop 0
	global_load_lds_dwordx4 v[6:7], off
	v_lshl_add_u64 v[6:7], v[4:5], 0, s[48:49]
	s_add_i32 s2, s81, s48
	s_sleep 3
	s_mov_b32 m0, s2
	s_nop 0
	global_load_lds_dwordx4 v[6:7], off
	v_lshl_add_u64 v[6:7], v[4:5], 0, s[50:51]
	s_add_i32 s2, s81, s50
	s_sleep 3
	s_mov_b32 m0, s2
	s_nop 0
	global_load_lds_dwordx4 v[6:7], off
	v_lshl_add_u64 v[6:7], v[4:5], 0, s[52:53]
	s_add_i32 s2, s81, s52
	s_sleep 3
	s_mov_b32 m0, s2
	s_nop 0
	global_load_lds_dwordx4 v[6:7], off
	v_lshl_add_u64 v[6:7], v[4:5], 0, s[54:55]
	s_add_i32 s2, s81, s67
	s_sleep 3
	s_mov_b32 m0, s2
	s_nop 0
	global_load_lds_dwordx4 v[6:7], off
	v_lshl_add_u64 v[6:7], v[4:5], 0, s[56:57]
	s_add_i32 s2, s81, s72
	s_sleep 3
	s_mov_b32 m0, s2
	s_nop 0
	global_load_lds_dwordx4 v[6:7], off
	v_lshl_add_u64 v[6:7], v[4:5], 0, s[58:59]
	s_add_i32 s2, s81, s73
	s_sleep 3
	s_mov_b32 m0, s2
	s_nop 0
	global_load_lds_dwordx4 v[6:7], off
	s_sleep 3
	v_lshl_add_u64 v[6:7], v[4:5], 0, s[60:61]
	s_add_i32 s2, s81, s74
	s_mov_b32 m0, s2
	s_nop 0
	global_load_lds_dwordx4 v[6:7], off
	v_cndmask_b32_e64 v6, 0, 1, s[64:65]
	v_cmp_ne_u32_e64 s[2:3], 1, v6
	s_andn2_b64 vcc, exec, s[64:65]
	s_sleep 3
	s_cbranch_vccnz .LBB0_661
	s_add_i32 s81, s77, s81
	v_lshl_add_u64 v[4:5], v[4:5], 0, s[62:63]
	s_mov_b32 m0, s81
	s_nop 0
	global_load_lds_dwordx4 v[4:5], off
	s_sleep 3
	s_branch .LBB0_661
.LBB0_664:
	v_readlane_b32 s4, v252, 41
	v_readlane_b32 s5, v252, 42
	s_add_i32 s67, s67, s76
	s_add_i32 s72, s72, s76
	v_lshl_add_u64 v[2:3], v[2:3], 0, s[4:5]
	v_lshl_add_u64 v[4:5], v[2:3], 0, s[46:47]
	s_add_i32 s4, s46, s76
	s_mov_b32 m0, s4
	s_nop 0
	global_load_lds_dwordx4 v[4:5], off
	v_lshl_add_u64 v[4:5], v[2:3], 0, s[48:49]
	s_sleep 3
	s_add_i32 s4, s48, s76
	s_mov_b32 m0, s4
	s_nop 0
	global_load_lds_dwordx4 v[4:5], off
	v_lshl_add_u64 v[4:5], v[2:3], 0, s[50:51]
	s_sleep 3
	s_add_i32 s4, s50, s76
	s_mov_b32 m0, s4
	s_nop 0
	global_load_lds_dwordx4 v[4:5], off
	v_lshl_add_u64 v[4:5], v[2:3], 0, s[52:53]
	s_sleep 3
	s_add_i32 s4, s52, s76
	s_mov_b32 m0, s4
	s_nop 0
	global_load_lds_dwordx4 v[4:5], off
	v_lshl_add_u64 v[4:5], v[2:3], 0, s[54:55]
	s_sleep 3
	s_mov_b32 m0, s67
	s_nop 0
	global_load_lds_dwordx4 v[4:5], off
	v_lshl_add_u64 v[4:5], v[2:3], 0, s[56:57]
	s_sleep 3
	s_mov_b32 m0, s72
	s_nop 0
	global_load_lds_dwordx4 v[4:5], off
	v_lshl_add_u64 v[4:5], v[2:3], 0, s[58:59]
	s_sleep 3
	s_add_i32 s73, s73, s76
	s_mov_b32 m0, s73
	s_nop 0
	global_load_lds_dwordx4 v[4:5], off
	s_sleep 3
	v_lshl_add_u64 v[4:5], v[2:3], 0, s[60:61]
	s_add_i32 s74, s74, s76
	s_mov_b32 m0, s74
	s_nop 0
	global_load_lds_dwordx4 v[4:5], off
	s_and_b64 vcc, exec, s[2:3]
	s_sleep 3
	s_cbranch_vccnz .LBB0_666
	s_add_i32 s2, s75, 0
	s_add_i32 s2, s2, 0x18800
	v_lshl_add_u64 v[2:3], v[2:3], 0, s[62:63]
	s_mov_b32 m0, s2
	s_nop 0
	global_load_lds_dwordx4 v[2:3], off
	s_sleep 3
